# attention loops: plus dead m0 save/restore pairs and in-place zero adds removed (on top of the max-tree trim)
# speedup vs baseline: 1.0068x; 1.0003x over previous
.LBB0_606:
	v_add_u32_e32 v166, s56, v195
	ds_read_b64_tr_b16 v[162:163], v166 offset:24576
	ds_read_b64_tr_b16 v[164:165], v166 offset:25088
	s_waitcnt lgkmcnt(9)
	v_mfma_f32_32x32x16_bf16 v[82:97], v[158:161], v[126:129], v[82:97]
	v_add_f32_e32 v102, v50, v51
	v_add_f32_e32 v102, v52, v102
	v_add_f32_e32 v102, v53, v102
	v_add_f32_e32 v102, v54, v102
	v_add_f32_e32 v102, v55, v102
	v_cvt_pk_bf16_f32 v122, v50, v51
	v_cvt_pk_bf16_f32 v123, v52, v53
	ds_read_b64_tr_b16 v[50:51], v166 offset:28672
	ds_read_b64_tr_b16 v[52:53], v166 offset:29184
	s_waitcnt lgkmcnt(10)
	v_mfma_f32_32x32x16_bf16 v[66:81], v[154:157], v[126:129], v[66:81]
	v_add_f32_e32 v102, v56, v102
	v_add_f32_e32 v102, v57, v102
	v_add_f32_e32 v102, v58, v102
	v_add_f32_e32 v102, v59, v102
	v_cvt_pk_bf16_f32 v124, v54, v55
	v_cvt_pk_bf16_f32 v125, v56, v57
	ds_read_b64_tr_b16 v[54:55], v166 offset:25600
	ds_read_b64_tr_b16 v[56:57], v166 offset:26112
	s_waitcnt lgkmcnt(11)
	v_mfma_f32_32x32x16_bf16 v[82:97], v[150:153], v[118:121], v[82:97]
	v_add_f32_e32 v102, v60, v102
	v_add_f32_e32 v102, v61, v102
	v_add_f32_e32 v102, v62, v102
	v_add_f32_e32 v102, v63, v102
	v_cvt_pk_bf16_f32 v114, v58, v59
	v_cvt_pk_bf16_f32 v115, v60, v61
	ds_read_b64_tr_b16 v[58:59], v166 offset:29696
	ds_read_b64_tr_b16 v[60:61], v166 offset:30208
	s_waitcnt lgkmcnt(12)
	v_mfma_f32_32x32x16_bf16 v[66:81], v[146:149], v[118:121], v[66:81]
	v_add_f32_e32 v102, v64, v102
	v_add_f32_e32 v102, v65, v102
	v_add_f32_e32 v102, v34, v102
	v_add_f32_e32 v102, v35, v102
	v_cvt_pk_bf16_f32 v116, v62, v63
	v_cvt_pk_bf16_f32 v117, v64, v65
	ds_read_b64_tr_b16 v[62:63], v166 offset:26624
	ds_read_b64_tr_b16 v[64:65], v166 offset:27136
	s_waitcnt lgkmcnt(13)
	v_mfma_f32_32x32x16_bf16 v[82:97], v[142:145], v[106:109], v[82:97]
	v_add_f32_e32 v102, v36, v102
	v_add_f32_e32 v102, v37, v102
	v_add_f32_e32 v102, v38, v102
	v_add_f32_e32 v102, v39, v102
	v_cvt_pk_bf16_f32 v110, v34, v35
	v_cvt_pk_bf16_f32 v111, v36, v37
	ds_read_b64_tr_b16 v[34:35], v166 offset:30720
	ds_read_b64_tr_b16 v[36:37], v166 offset:31232
	s_waitcnt lgkmcnt(14)
	v_mfma_f32_32x32x16_bf16 v[66:81], v[138:141], v[106:109], v[66:81]
	v_add_f32_e32 v102, v40, v102
	v_add_f32_e32 v102, v41, v102
	v_add_f32_e32 v102, v42, v102
	v_add_f32_e32 v102, v43, v102
	v_cvt_pk_bf16_f32 v112, v38, v39
	v_cvt_pk_bf16_f32 v113, v40, v41
	ds_read_b64_tr_b16 v[38:39], v166 offset:27648
	ds_read_b64_tr_b16 v[40:41], v166 offset:28160
	s_waitcnt lgkmcnt(14)
	v_mfma_f32_32x32x16_bf16 v[82:97], v[134:137], v[98:101], v[82:97]
	v_add_f32_e32 v102, v44, v102
	v_add_f32_e32 v102, v45, v102
	v_add_f32_e32 v102, v46, v102
	v_add_f32_e32 v134, v47, v102
	v_cvt_pk_bf16_f32 v102, v42, v43
	v_cvt_pk_bf16_f32 v103, v44, v45
	ds_read_b64_tr_b16 v[42:43], v166 offset:31744
	ds_read_b64_tr_b16 v[44:45], v166 offset:32256
	v_mfma_f32_32x32x16_bf16 v[66:81], v[130:133], v[98:101], v[66:81]
	v_add_f32_e32 v104, v48, v134
	v_add_f32_e32 v104, v49, v104
	v_add_f32_e32 v130, 0, v104
	v_cvt_pk_bf16_f32 v104, v46, v47
	v_cvt_pk_bf16_f32 v105, v48, v49
	s_add_i32 s30, s31, s33
	s_sub_i32 s0, s30, 64
	v_mad_i64_i32 v[46:47], s[0:1], s0, v217, v[174:175]
	s_add_i32 s0, s35, s21
	s_cmp_lt_u32 s34, 3
	s_mov_b32 m0, s0
	s_nop 0
	global_load_lds_dwordx4 v[46:47], off
	s_cselect_b32 s0, s7, s9
	s_add_i32 s0, s0, s33
	v_mad_i64_i32 v[46:47], s[0:1], s0, v217, v[176:177]
	s_add_i32 s0, s6, s22
	s_mov_b32 m0, s0
	s_nop 0
	global_load_lds_dwordx4 v[46:47], off
	v_max_f32_e32 v46, v82, v83
	v_max3_f32 v47, v84, v85, v67
	v_max3_f32 v46, v46, v66, v68
	v_max3_f32 v46, v46, v69, v86
	v_max3_f32 v47, v47, v88, v89
	v_max3_f32 v46, v46, v87, v70
	v_max3_f32 v47, v47, v72, v73
	v_max3_f32 v46, v46, v71, v90
	v_max3_f32 v47, v47, v92, v93
	v_max3_f32 v46, v46, v91, v74
	v_max3_f32 v47, v47, v76, v77
	v_max3_f32 v46, v46, v75, v94
	v_max3_f32 v47, v47, v96, v97
	v_max3_f32 v46, v46, v95, v78
	v_max3_f32 v47, v47, v80, v81
	v_max3_f32 v46, v46, v79, v47
	v_mov_b32_e32 v47, v46
	s_nop 1
	v_permlane32_swap_b32_e32 v46, v47
	v_max_f32_e32 v46, v46, v47
	v_cmp_lt_f32_e32 vcc, s51, v46
	s_cmp_lg_u64 vcc, 0
	v_add_f32_e32 v166, v200, v130
	s_cselect_b64 s[0:1], -1, 0
	s_cbranch_vccnz .LBB0_622

.LBB0_617:
	s_add_i32 s0, s6, 0x2000
	s_cmpk_lg_i32 s6, 0x4000
	s_cselect_b32 s29, s0, 0
	v_add_u32_e32 v167, s35, v195
	ds_read_b64_tr_b16 v[162:163], v167 offset:24576
	ds_read_b64_tr_b16 v[164:165], v167 offset:25088
	s_waitcnt lgkmcnt(9)
	v_mfma_f32_32x32x16_bf16 v[50:65], v[158:161], v[126:129], v[50:65]
	v_add_f32_e32 v102, v82, v83
	v_add_f32_e32 v102, v84, v102
	v_add_f32_e32 v102, v85, v102
	v_add_f32_e32 v102, v86, v102
	v_add_f32_e32 v102, v87, v102
	v_cvt_pk_bf16_f32 v122, v82, v83
	v_cvt_pk_bf16_f32 v123, v84, v85
	ds_read_b64_tr_b16 v[82:83], v167 offset:28672
	ds_read_b64_tr_b16 v[84:85], v167 offset:29184
	s_waitcnt lgkmcnt(10)
	v_mfma_f32_32x32x16_bf16 v[34:49], v[154:157], v[126:129], v[34:49]
	v_add_f32_e32 v102, v88, v102
	v_add_f32_e32 v102, v89, v102
	v_add_f32_e32 v102, v90, v102
	v_add_f32_e32 v102, v91, v102
	v_cvt_pk_bf16_f32 v124, v86, v87
	v_cvt_pk_bf16_f32 v125, v88, v89
	ds_read_b64_tr_b16 v[86:87], v167 offset:25600
	ds_read_b64_tr_b16 v[88:89], v167 offset:26112
	s_waitcnt lgkmcnt(11)
	v_mfma_f32_32x32x16_bf16 v[50:65], v[150:153], v[118:121], v[50:65]
	v_add_f32_e32 v102, v92, v102
	v_add_f32_e32 v102, v93, v102
	v_add_f32_e32 v102, v94, v102
	v_add_f32_e32 v102, v95, v102
	v_cvt_pk_bf16_f32 v114, v90, v91
	v_cvt_pk_bf16_f32 v115, v92, v93
	ds_read_b64_tr_b16 v[90:91], v167 offset:29696
	ds_read_b64_tr_b16 v[92:93], v167 offset:30208
	s_waitcnt lgkmcnt(12)
	v_mfma_f32_32x32x16_bf16 v[34:49], v[146:149], v[118:121], v[34:49]
	v_add_f32_e32 v102, v96, v102
	v_add_f32_e32 v102, v97, v102
	v_add_f32_e32 v102, v66, v102
	v_add_f32_e32 v102, v67, v102
	v_cvt_pk_bf16_f32 v116, v94, v95
	v_cvt_pk_bf16_f32 v117, v96, v97
	ds_read_b64_tr_b16 v[94:95], v167 offset:26624
	ds_read_b64_tr_b16 v[96:97], v167 offset:27136
	s_waitcnt lgkmcnt(13)
	v_mfma_f32_32x32x16_bf16 v[50:65], v[142:145], v[106:109], v[50:65]
	v_add_f32_e32 v102, v68, v102
	v_add_f32_e32 v102, v69, v102
	v_add_f32_e32 v102, v70, v102
	v_add_f32_e32 v102, v71, v102
	v_cvt_pk_bf16_f32 v110, v66, v67
	v_cvt_pk_bf16_f32 v111, v68, v69
	ds_read_b64_tr_b16 v[66:67], v167 offset:30720
	ds_read_b64_tr_b16 v[68:69], v167 offset:31232
	s_waitcnt lgkmcnt(14)
	v_mfma_f32_32x32x16_bf16 v[34:49], v[138:141], v[106:109], v[34:49]
	v_add_f32_e32 v102, v72, v102
	v_add_f32_e32 v102, v73, v102
	v_add_f32_e32 v102, v74, v102
	v_add_f32_e32 v102, v75, v102
	v_cvt_pk_bf16_f32 v112, v70, v71
	v_cvt_pk_bf16_f32 v113, v72, v73
	ds_read_b64_tr_b16 v[70:71], v167 offset:27648
	ds_read_b64_tr_b16 v[72:73], v167 offset:28160
	s_waitcnt lgkmcnt(14)
	v_mfma_f32_32x32x16_bf16 v[50:65], v[134:137], v[98:101], v[50:65]
	v_add_f32_e32 v102, v76, v102
	v_add_f32_e32 v102, v77, v102
	v_add_f32_e32 v102, v78, v102
	v_add_f32_e32 v134, v79, v102
	v_cvt_pk_bf16_f32 v102, v74, v75
	v_cvt_pk_bf16_f32 v103, v76, v77
	ds_read_b64_tr_b16 v[74:75], v167 offset:31744
	ds_read_b64_tr_b16 v[76:77], v167 offset:32256
	v_mfma_f32_32x32x16_bf16 v[34:49], v[130:133], v[98:101], v[34:49]
	v_add_f32_e32 v104, v80, v134
	v_add_f32_e32 v104, v81, v104
	v_add_f32_e32 v130, 0, v104
	v_cvt_pk_bf16_f32 v104, v78, v79
	v_cvt_pk_bf16_f32 v105, v80, v81
	v_mad_i64_i32 v[78:79], s[0:1], s30, v217, v[174:175]
	s_add_i32 s0, s6, s21
	s_cmp_lt_u32 s34, 2
	s_mov_b32 m0, s0
	s_nop 0
	global_load_lds_dwordx4 v[78:79], off
	s_cselect_b32 s0, s8, s10
	s_add_i32 s0, s0, s33
	v_mad_i64_i32 v[78:79], s[0:1], s0, v217, v[176:177]
	s_add_i32 s0, s29, s22
	s_mov_b32 m0, s0
	s_nop 0
	global_load_lds_dwordx4 v[78:79], off
	v_max_f32_e32 v78, v50, v51
	v_max3_f32 v79, v52, v53, v35
	v_max3_f32 v78, v78, v34, v36
	v_max3_f32 v78, v78, v37, v54
	v_max3_f32 v79, v79, v56, v57
	v_max3_f32 v78, v78, v55, v38
	v_max3_f32 v79, v79, v40, v41
	v_max3_f32 v78, v78, v39, v58
	v_max3_f32 v79, v79, v60, v61
	v_max3_f32 v78, v78, v59, v42
	v_max3_f32 v79, v79, v44, v45
	v_max3_f32 v78, v78, v43, v62
	v_max3_f32 v79, v79, v64, v65
	v_max3_f32 v78, v78, v63, v46
	v_max3_f32 v79, v79, v48, v49
	v_max3_f32 v78, v78, v47, v79
	v_mov_b32_e32 v79, v78
	s_nop 1
	v_permlane32_swap_b32_e32 v78, v79
	v_max_f32_e32 v78, v78, v79
	v_cmp_lt_f32_e32 vcc, s51, v78
	s_cmp_lg_u64 vcc, 0
	v_add_f32_e32 v200, v166, v130
	s_cselect_b64 s[0:1], -1, 0
	s_cbranch_vccnz .LBB0_625

.LBB0_637:
	s_add_i32 s0, s28, 0xffffff80
	v_mad_i64_i32 v[46:47], s[0:1], s0, v217, v[176:177]
	s_add_i32 s0, s30, s22
	s_mov_b32 m0, s0
	s_nop 0
	global_load_lds_dwordx4 v[46:47], off
	v_max_f32_e32 v46, v82, v83
	v_max3_f32 v47, v84, v85, v67
	v_max3_f32 v46, v46, v66, v68
	v_max3_f32 v46, v46, v69, v86
	v_max3_f32 v47, v47, v88, v89
	v_max3_f32 v46, v46, v87, v70
	v_max3_f32 v47, v47, v72, v73
	v_max3_f32 v46, v46, v71, v90
	v_max3_f32 v47, v47, v92, v93
	v_max3_f32 v46, v46, v91, v74
	v_max3_f32 v47, v47, v76, v77
	v_max3_f32 v46, v46, v75, v94
	v_max3_f32 v47, v47, v96, v97
	v_max3_f32 v46, v46, v95, v78
	v_max3_f32 v47, v47, v80, v81
	v_max3_f32 v46, v46, v79, v47
	v_mov_b32_e32 v47, v46
	s_nop 1
	v_permlane32_swap_b32_e32 v46, v47
	v_max_f32_e32 v46, v46, v47
	v_cmp_lt_f32_e32 vcc, s51, v46
	s_cmp_lg_u64 vcc, 0
	v_add_f32_e32 v200, v200, v130
	s_cselect_b64 s[0:1], -1, 0
	s_cbranch_vccnz .LBB0_678

.LBB0_651:
	v_add_u32_e32 v186, s29, v195
	ds_read_b64_tr_b16 v[170:171], v186 offset:24576
	ds_read_b64_tr_b16 v[172:173], v186 offset:25088
	s_waitcnt lgkmcnt(9)
	v_mfma_f32_32x32x16_bf16 v[50:65], v[158:161], v[126:129], v[50:65]
	v_add_f32_e32 v102, v82, v83
	v_add_f32_e32 v102, v84, v102
	v_add_f32_e32 v102, v85, v102
	v_add_f32_e32 v102, v86, v102
	v_add_f32_e32 v102, v87, v102
	v_cvt_pk_bf16_f32 v122, v82, v83
	v_cvt_pk_bf16_f32 v123, v84, v85
	ds_read_b64_tr_b16 v[166:167], v186 offset:28672
	ds_read_b64_tr_b16 v[168:169], v186 offset:29184
	s_waitcnt lgkmcnt(10)
	v_mfma_f32_32x32x16_bf16 v[34:49], v[154:157], v[126:129], v[34:49]
	v_add_f32_e32 v82, v88, v102
	v_add_f32_e32 v82, v89, v82
	v_add_f32_e32 v82, v90, v82
	v_add_f32_e32 v82, v91, v82
	v_cvt_pk_bf16_f32 v124, v86, v87
	v_cvt_pk_bf16_f32 v125, v88, v89
	ds_read_b64_tr_b16 v[162:163], v186 offset:25600
	ds_read_b64_tr_b16 v[164:165], v186 offset:26112
	s_waitcnt lgkmcnt(11)
	v_mfma_f32_32x32x16_bf16 v[50:65], v[150:153], v[118:121], v[50:65]
	v_add_f32_e32 v82, v92, v82
	v_add_f32_e32 v82, v93, v82
	v_add_f32_e32 v82, v94, v82
	v_add_f32_e32 v82, v95, v82
	v_cvt_pk_bf16_f32 v114, v90, v91
	v_cvt_pk_bf16_f32 v115, v92, v93
	ds_read_b64_tr_b16 v[90:91], v186 offset:29696
	ds_read_b64_tr_b16 v[92:93], v186 offset:30208
	s_waitcnt lgkmcnt(12)
	v_mfma_f32_32x32x16_bf16 v[34:49], v[146:149], v[118:121], v[34:49]
	v_add_f32_e32 v82, v96, v82
	v_add_f32_e32 v82, v97, v82
	v_add_f32_e32 v82, v66, v82
	v_add_f32_e32 v82, v67, v82
	v_cvt_pk_bf16_f32 v116, v94, v95
	v_cvt_pk_bf16_f32 v117, v96, v97
	ds_read_b64_tr_b16 v[86:87], v186 offset:26624
	ds_read_b64_tr_b16 v[88:89], v186 offset:27136
	s_waitcnt lgkmcnt(13)
	v_mfma_f32_32x32x16_bf16 v[50:65], v[142:145], v[106:109], v[50:65]
	v_add_f32_e32 v82, v68, v82
	v_add_f32_e32 v82, v69, v82
	v_add_f32_e32 v82, v70, v82
	v_add_f32_e32 v94, v71, v82
	v_cvt_pk_bf16_f32 v110, v66, v67
	v_cvt_pk_bf16_f32 v111, v68, v69
	ds_read_b64_tr_b16 v[82:83], v186 offset:30720
	ds_read_b64_tr_b16 v[84:85], v186 offset:31232
	s_waitcnt lgkmcnt(14)
	v_mfma_f32_32x32x16_bf16 v[34:49], v[138:141], v[106:109], v[34:49]
	v_add_f32_e32 v66, v72, v94
	v_add_f32_e32 v66, v73, v66
	v_add_f32_e32 v66, v74, v66
	v_add_f32_e32 v66, v75, v66
	v_cvt_pk_bf16_f32 v112, v70, v71
	v_cvt_pk_bf16_f32 v113, v72, v73
	ds_read_b64_tr_b16 v[70:71], v186 offset:27648
	ds_read_b64_tr_b16 v[72:73], v186 offset:28160
	s_waitcnt lgkmcnt(14)
	v_mfma_f32_32x32x16_bf16 v[50:65], v[134:137], v[98:101], v[50:65]
	v_add_f32_e32 v66, v76, v66
	v_add_f32_e32 v66, v77, v66
	v_add_f32_e32 v66, v78, v66
	v_add_f32_e32 v94, v79, v66
	v_cvt_pk_bf16_f32 v102, v74, v75
	v_cvt_pk_bf16_f32 v103, v76, v77
	ds_read_b64_tr_b16 v[66:67], v186 offset:31744
	ds_read_b64_tr_b16 v[68:69], v186 offset:32256
	v_mfma_f32_32x32x16_bf16 v[34:49], v[130:133], v[98:101], v[34:49]
	v_add_f32_e32 v74, v80, v94
	v_add_f32_e32 v74, v81, v74
	v_cvt_pk_bf16_f32 v104, v78, v79
	v_cvt_pk_bf16_f32 v105, v80, v81
	s_cmp_ge_u32 s35, s34
	s_cselect_b64 s[0:1], -1, 0
	s_and_b64 vcc, exec, s[0:1]
	s_cbranch_vccnz .LBB0_653
	s_add_i32 s6, s28, 64
	v_mad_i64_i32 v[76:77], s[6:7], s6, v217, v[174:175]
	s_add_i32 s6, s30, s21
	s_mov_b32 m0, s6
	s_nop 0
	global_load_lds_dwordx4 v[76:77], off

.LBB0_690:
	v_add_u32_e32 v166, s30, v195
	ds_read_b64_tr_b16 v[162:163], v166 offset:24576
	ds_read_b64_tr_b16 v[164:165], v166 offset:25088
	s_waitcnt lgkmcnt(9)
	v_mfma_f32_32x32x16_bf16 v[82:97], v[158:161], v[126:129], v[82:97]
	v_add_f32_e32 v102, v50, v51
	v_add_f32_e32 v102, v52, v102
	v_add_f32_e32 v102, v53, v102
	v_add_f32_e32 v102, v54, v102
	v_add_f32_e32 v102, v55, v102
	v_cvt_pk_bf16_f32 v122, v50, v51
	v_cvt_pk_bf16_f32 v123, v52, v53
	ds_read_b64_tr_b16 v[50:51], v166 offset:28672
	ds_read_b64_tr_b16 v[52:53], v166 offset:29184
	s_waitcnt lgkmcnt(10)
	v_mfma_f32_32x32x16_bf16 v[66:81], v[154:157], v[126:129], v[66:81]
	v_add_f32_e32 v102, v56, v102
	v_add_f32_e32 v102, v57, v102
	v_add_f32_e32 v102, v58, v102
	v_add_f32_e32 v102, v59, v102
	v_cvt_pk_bf16_f32 v124, v54, v55
	v_cvt_pk_bf16_f32 v125, v56, v57
	ds_read_b64_tr_b16 v[54:55], v166 offset:25600
	ds_read_b64_tr_b16 v[56:57], v166 offset:26112
	s_waitcnt lgkmcnt(11)
	v_mfma_f32_32x32x16_bf16 v[82:97], v[150:153], v[118:121], v[82:97]
	v_add_f32_e32 v102, v60, v102
	v_add_f32_e32 v102, v61, v102
	v_add_f32_e32 v102, v62, v102
	v_add_f32_e32 v102, v63, v102
	v_cvt_pk_bf16_f32 v114, v58, v59
	v_cvt_pk_bf16_f32 v115, v60, v61
	ds_read_b64_tr_b16 v[58:59], v166 offset:29696
	ds_read_b64_tr_b16 v[60:61], v166 offset:30208
	s_waitcnt lgkmcnt(12)
	v_mfma_f32_32x32x16_bf16 v[66:81], v[146:149], v[118:121], v[66:81]
	v_add_f32_e32 v102, v64, v102
	v_add_f32_e32 v102, v65, v102
	v_add_f32_e32 v102, v34, v102
	v_add_f32_e32 v102, v35, v102
	v_cvt_pk_bf16_f32 v116, v62, v63
	v_cvt_pk_bf16_f32 v117, v64, v65
	ds_read_b64_tr_b16 v[62:63], v166 offset:26624
	ds_read_b64_tr_b16 v[64:65], v166 offset:27136
	s_waitcnt lgkmcnt(13)
	v_mfma_f32_32x32x16_bf16 v[82:97], v[142:145], v[106:109], v[82:97]
	v_add_f32_e32 v102, v36, v102
	v_add_f32_e32 v102, v37, v102
	v_add_f32_e32 v102, v38, v102
	v_add_f32_e32 v102, v39, v102
	v_cvt_pk_bf16_f32 v110, v34, v35
	v_cvt_pk_bf16_f32 v111, v36, v37
	ds_read_b64_tr_b16 v[34:35], v166 offset:30720
	ds_read_b64_tr_b16 v[36:37], v166 offset:31232
	s_waitcnt lgkmcnt(14)
	v_mfma_f32_32x32x16_bf16 v[66:81], v[138:141], v[106:109], v[66:81]
	v_add_f32_e32 v102, v40, v102
	v_add_f32_e32 v102, v41, v102
	v_add_f32_e32 v102, v42, v102
	v_add_f32_e32 v102, v43, v102
	v_cvt_pk_bf16_f32 v112, v38, v39
	v_cvt_pk_bf16_f32 v113, v40, v41
	ds_read_b64_tr_b16 v[38:39], v166 offset:27648
	ds_read_b64_tr_b16 v[40:41], v166 offset:28160
	s_waitcnt lgkmcnt(14)
	v_mfma_f32_32x32x16_bf16 v[82:97], v[134:137], v[98:101], v[82:97]
	v_add_f32_e32 v102, v44, v102
	v_add_f32_e32 v102, v45, v102
	v_add_f32_e32 v102, v46, v102
	v_add_f32_e32 v106, v47, v102
	v_cvt_pk_bf16_f32 v102, v42, v43
	v_cvt_pk_bf16_f32 v103, v44, v45
	ds_read_b64_tr_b16 v[42:43], v166 offset:31744
	ds_read_b64_tr_b16 v[44:45], v166 offset:32256
	v_mfma_f32_32x32x16_bf16 v[66:81], v[130:133], v[98:101], v[66:81]
	v_add_f32_e32 v98, v48, v106
	v_add_f32_e32 v98, v49, v98
	v_cvt_pk_bf16_f32 v104, v46, v47
	v_cvt_pk_bf16_f32 v105, v48, v49
	v_max_f32_e32 v46, v82, v83
	s_nop 3
	v_max3_f32 v47, v84, v85, v67
	v_max3_f32 v46, v46, v66, v68
	v_max3_f32 v46, v46, v69, v86
	v_max3_f32 v47, v47, v88, v89
	v_max3_f32 v46, v46, v87, v70
	v_max3_f32 v47, v47, v72, v73
	v_max3_f32 v46, v46, v71, v90
	v_max3_f32 v47, v47, v92, v93
	v_max3_f32 v46, v46, v91, v74
	v_max3_f32 v47, v47, v76, v77
	v_max3_f32 v46, v46, v75, v94
	v_max3_f32 v47, v47, v96, v97
	v_max3_f32 v48, v46, v95, v78
	v_max3_f32 v47, v47, v80, v81
	v_max3_f32 v47, v48, v79, v47
	v_mov_b32_e32 v48, v47
	s_nop 1
	v_permlane32_swap_b32_e32 v47, v48
	v_max_f32_e32 v47, v47, v48
	v_cmp_lt_f32_e32 vcc, s51, v47
	s_cmp_lg_u64 vcc, 0
	v_add_f32_e32 v46, v200, v98
	s_cselect_b64 s[0:1], -1, 0
	s_cbranch_vccnz .LBB0_695

.LBB0_707:
	s_add_i32 s22, s23, 2
	v_add_u32_e32 v186, s0, v207
	ds_read_b64_tr_b16 v[178:179], v186 offset:24576
	ds_read_b64_tr_b16 v[180:181], v186 offset:25088
	s_waitcnt lgkmcnt(9)
	v_mfma_f32_32x32x16_bf16 v[98:113], v[174:177], v[142:145], v[34:49]
	v_add_f32_e32 v82, v66, v67
	v_add_f32_e32 v82, v68, v82
	v_add_f32_e32 v82, v69, v82
	v_add_f32_e32 v82, v70, v82
	v_add_f32_e32 v82, v71, v82
	v_cvt_pk_bf16_f32 v134, v66, v67
	v_cvt_pk_bf16_f32 v135, v68, v69
	ds_read_b64_tr_b16 v[174:175], v186 offset:28672
	ds_read_b64_tr_b16 v[176:177], v186 offset:29184
	v_add_f32_e32 v66, v72, v82
	s_waitcnt lgkmcnt(10)
	v_mfma_f32_32x32x16_bf16 v[82:97], v[170:173], v[142:145], v[34:49]
	v_add_f32_e32 v66, v73, v66
	v_add_f32_e32 v66, v74, v66
	v_add_f32_e32 v114, v75, v66
	v_cvt_pk_bf16_f32 v136, v70, v71
	v_cvt_pk_bf16_f32 v137, v72, v73
	ds_read_b64_tr_b16 v[66:67], v186 offset:25600
	ds_read_b64_tr_b16 v[68:69], v186 offset:26112
	s_waitcnt lgkmcnt(11)
	v_mfma_f32_32x32x16_bf16 v[98:113], v[166:169], v[138:141], v[98:113]
	v_add_f32_e32 v70, v76, v114
	v_add_f32_e32 v70, v77, v70
	v_add_f32_e32 v70, v78, v70
	v_add_f32_e32 v114, v79, v70
	v_cvt_pk_bf16_f32 v126, v74, v75
	v_cvt_pk_bf16_f32 v127, v76, v77
	ds_read_b64_tr_b16 v[70:71], v186 offset:29696
	ds_read_b64_tr_b16 v[72:73], v186 offset:30208
	s_waitcnt lgkmcnt(12)
	v_mfma_f32_32x32x16_bf16 v[82:97], v[162:165], v[138:141], v[82:97]
	v_add_f32_e32 v74, v80, v114
	v_add_f32_e32 v74, v81, v74
	v_add_f32_e32 v74, v50, v74
	v_add_f32_e32 v114, v51, v74
	v_cvt_pk_bf16_f32 v128, v78, v79
	v_cvt_pk_bf16_f32 v129, v80, v81
	ds_read_b64_tr_b16 v[74:75], v186 offset:26624
	ds_read_b64_tr_b16 v[76:77], v186 offset:27136
	s_waitcnt lgkmcnt(13)
	v_mfma_f32_32x32x16_bf16 v[98:113], v[158:161], v[130:133], v[98:113]
	v_add_f32_e32 v78, v52, v114
	v_add_f32_e32 v78, v53, v78
	v_add_f32_e32 v78, v54, v78
	v_add_f32_e32 v78, v55, v78
	v_cvt_pk_bf16_f32 v118, v50, v51
	v_cvt_pk_bf16_f32 v119, v52, v53
	ds_read_b64_tr_b16 v[50:51], v186 offset:30720
	ds_read_b64_tr_b16 v[52:53], v186 offset:31232
	s_waitcnt lgkmcnt(14)
	v_mfma_f32_32x32x16_bf16 v[82:97], v[154:157], v[130:133], v[82:97]
	v_add_f32_e32 v78, v56, v78
	v_add_f32_e32 v78, v57, v78
	v_add_f32_e32 v78, v58, v78
	v_add_f32_e32 v78, v59, v78
	v_cvt_pk_bf16_f32 v120, v54, v55
	v_cvt_pk_bf16_f32 v121, v56, v57
	ds_read_b64_tr_b16 v[54:55], v186 offset:27648
	ds_read_b64_tr_b16 v[56:57], v186 offset:28160
	s_waitcnt lgkmcnt(14)
	v_mfma_f32_32x32x16_bf16 v[98:113], v[150:153], v[122:125], v[98:113]
	v_add_f32_e32 v78, v60, v78
	v_add_f32_e32 v78, v61, v78
	v_add_f32_e32 v78, v62, v78
	v_add_f32_e32 v78, v63, v78
	v_cvt_pk_bf16_f32 v114, v58, v59
	v_cvt_pk_bf16_f32 v115, v60, v61
	ds_read_b64_tr_b16 v[58:59], v186 offset:31744
	ds_read_b64_tr_b16 v[60:61], v186 offset:32256
	v_mfma_f32_32x32x16_bf16 v[82:97], v[146:149], v[122:125], v[82:97]
	v_add_f32_e32 v78, v64, v78
	v_add_f32_e32 v78, v65, v78
	v_cvt_pk_bf16_f32 v116, v62, v63
	v_cvt_pk_bf16_f32 v117, v64, v65
	s_cmpk_gt_u32 s22, 0x7c
	s_cselect_b64 s[0:1], -1, 0
	s_cmpk_lt_u32 s22, 0x7d
	s_cselect_b32 s4, 0, 0xffffff80
	s_cselect_b32 s5, s9, s20
	s_add_i32 s4, s4, s23
	s_lshl_b32 s4, s4, 6
	s_add_i32 s4, s4, s5
	s_addk_i32 s4, 0x140
	v_mad_i64_i32 v[62:63], s[4:5], s4, v217, v[192:193]
	s_add_i32 s4, s24, s18
	s_mov_b32 m0, s4
	s_nop 0
	global_load_lds_dwordx4 v[62:63], off
	v_max_f32_e32 v62, v98, v99
	v_max3_f32 v63, v100, v101, v83
	v_max3_f32 v62, v62, v82, v84
	v_max3_f32 v62, v62, v85, v102
	v_max3_f32 v63, v63, v104, v105
	v_max3_f32 v62, v62, v103, v86
	v_max3_f32 v63, v63, v88, v89
	v_max3_f32 v62, v62, v87, v106
	v_max3_f32 v63, v63, v108, v109
	v_max3_f32 v62, v62, v107, v90
	v_max3_f32 v63, v63, v92, v93
	v_max3_f32 v62, v62, v91, v110
	v_max3_f32 v63, v63, v112, v113
	v_max3_f32 v62, v62, v111, v94
	v_max3_f32 v63, v63, v96, v97
	v_max3_f32 v62, v62, v95, v63
	v_mov_b32_e32 v63, v62
	s_nop 1
	v_permlane32_swap_b32_e32 v62, v63
	v_max_f32_e32 v62, v62, v63
	s_add_i32 s4, s21, s19
	s_mov_b32 m0, s4
	s_nop 0
	global_load_lds_dwordx4 v[196:197], off
	v_cmp_lt_f32_e32 vcc, s51, v62
	s_cmp_lg_u64 vcc, 0
	v_add_f32_e32 v224, v224, v78
	s_cselect_b64 s[4:5], -1, 0
	s_cbranch_vccnz .LBB0_715

.LBB0_710:
	s_add_i32 s4, s21, 0x2000
	s_cmpk_lg_i32 s21, 0x4000
	s_cselect_b32 s25, s4, 0
	v_add_u32_e32 v186, s24, v207
	ds_read_b64_tr_b16 v[150:151], v186 offset:24576
	ds_read_b64_tr_b16 v[152:153], v186 offset:25088
	s_waitcnt lgkmcnt(9)
	v_mfma_f32_32x32x16_bf16 v[66:81], v[62:65], v[142:145], v[34:49]
	v_add_f32_e32 v50, v98, v99
	v_add_f32_e32 v50, v100, v50
	v_add_f32_e32 v50, v101, v50
	v_add_f32_e32 v50, v102, v50
	v_add_f32_e32 v50, v103, v50
	v_cvt_pk_bf16_f32 v134, v98, v99
	v_cvt_pk_bf16_f32 v135, v100, v101
	ds_read_b64_tr_b16 v[146:147], v186 offset:28672
	ds_read_b64_tr_b16 v[148:149], v186 offset:29184
	v_add_f32_e32 v50, v104, v50
	v_add_f32_e32 v50, v105, v50
	v_add_f32_e32 v50, v106, v50
	v_add_f32_e32 v114, v107, v50
	s_waitcnt lgkmcnt(10)
	v_mfma_f32_32x32x16_bf16 v[50:65], v[174:177], v[142:145], v[34:49]
	v_cvt_pk_bf16_f32 v136, v102, v103
	v_cvt_pk_bf16_f32 v137, v104, v105
	ds_read_b64_tr_b16 v[98:99], v186 offset:25600
	ds_read_b64_tr_b16 v[100:101], v186 offset:26112
	s_waitcnt lgkmcnt(11)
	v_mfma_f32_32x32x16_bf16 v[66:81], v[178:181], v[138:141], v[66:81]
	v_add_f32_e32 v102, v108, v114
	v_add_f32_e32 v102, v109, v102
	v_add_f32_e32 v102, v110, v102
	v_add_f32_e32 v114, v111, v102
	v_cvt_pk_bf16_f32 v126, v106, v107
	v_cvt_pk_bf16_f32 v127, v108, v109
	ds_read_b64_tr_b16 v[102:103], v186 offset:29696
	ds_read_b64_tr_b16 v[104:105], v186 offset:30208
	s_waitcnt lgkmcnt(12)
	v_mfma_f32_32x32x16_bf16 v[50:65], v[170:173], v[138:141], v[50:65]
	v_add_f32_e32 v106, v112, v114
	v_add_f32_e32 v106, v113, v106
	v_add_f32_e32 v106, v82, v106
	v_add_f32_e32 v114, v83, v106
	v_cvt_pk_bf16_f32 v128, v110, v111
	v_cvt_pk_bf16_f32 v129, v112, v113
	ds_read_b64_tr_b16 v[106:107], v186 offset:26624
	ds_read_b64_tr_b16 v[108:109], v186 offset:27136
	s_waitcnt lgkmcnt(13)
	v_mfma_f32_32x32x16_bf16 v[66:81], v[166:169], v[130:133], v[66:81]
	v_add_f32_e32 v110, v84, v114
	v_add_f32_e32 v110, v85, v110
	v_add_f32_e32 v110, v86, v110
	v_add_f32_e32 v110, v87, v110
	v_cvt_pk_bf16_f32 v118, v82, v83
	v_cvt_pk_bf16_f32 v119, v84, v85
	ds_read_b64_tr_b16 v[82:83], v186 offset:30720
	ds_read_b64_tr_b16 v[84:85], v186 offset:31232
	s_waitcnt lgkmcnt(14)
	v_mfma_f32_32x32x16_bf16 v[50:65], v[162:165], v[130:133], v[50:65]
	v_add_f32_e32 v110, v88, v110
	v_add_f32_e32 v110, v89, v110
	v_add_f32_e32 v110, v90, v110
	v_add_f32_e32 v110, v91, v110
	v_cvt_pk_bf16_f32 v120, v86, v87
	v_cvt_pk_bf16_f32 v121, v88, v89
	ds_read_b64_tr_b16 v[86:87], v186 offset:27648
	ds_read_b64_tr_b16 v[88:89], v186 offset:28160
	s_waitcnt lgkmcnt(14)
	v_mfma_f32_32x32x16_bf16 v[66:81], v[158:161], v[122:125], v[66:81]
	v_add_f32_e32 v110, v92, v110
	v_add_f32_e32 v110, v93, v110
	v_add_f32_e32 v110, v94, v110
	v_add_f32_e32 v110, v95, v110
	v_cvt_pk_bf16_f32 v114, v90, v91
	v_cvt_pk_bf16_f32 v115, v92, v93
	ds_read_b64_tr_b16 v[90:91], v186 offset:31744
	ds_read_b64_tr_b16 v[92:93], v186 offset:32256
	v_mfma_f32_32x32x16_bf16 v[50:65], v[154:157], v[122:125], v[50:65]
	v_add_f32_e32 v110, v96, v110
	v_add_f32_e32 v110, v97, v110
	v_cvt_pk_bf16_f32 v116, v94, v95
	v_cvt_pk_bf16_f32 v117, v96, v97
	s_cmpk_lt_u32 s22, 0x7c
	s_cselect_b32 s4, 0, 0xffffff80
	s_cselect_b32 s5, s9, s20
	s_add_i32 s4, s4, s23
	s_lshl_b32 s4, s4, 6
	s_add_i32 s4, s4, s5
	s_addk_i32 s4, 0x180
	v_mad_i64_i32 v[94:95], s[4:5], s4, v217, v[192:193]
	s_add_i32 s4, s21, s18
	s_mov_b32 m0, s4
	s_nop 0
	global_load_lds_dwordx4 v[94:95], off
	v_lshl_add_u64 v[94:95], v[196:197], 0, s[30:31]
	s_add_i32 s4, s25, s19
	s_mov_b32 m0, s4
	s_nop 0
	global_load_lds_dwordx4 v[94:95], off
	v_max_f32_e32 v94, v66, v67
	v_max3_f32 v95, v68, v69, v51
	v_max3_f32 v94, v94, v50, v52
	v_max3_f32 v94, v94, v53, v70
	v_max3_f32 v95, v95, v72, v73
	v_max3_f32 v94, v94, v71, v54
	v_max3_f32 v95, v95, v56, v57
	v_max3_f32 v94, v94, v55, v74
	v_max3_f32 v95, v95, v76, v77
	v_max3_f32 v94, v94, v75, v58
	v_max3_f32 v95, v95, v60, v61
	v_max3_f32 v94, v94, v59, v78
	v_max3_f32 v95, v95, v80, v81
	v_max3_f32 v94, v94, v79, v62
	v_max3_f32 v95, v95, v64, v65
	v_max3_f32 v94, v94, v63, v95
	v_mov_b32_e32 v95, v94
	s_nop 1
	v_permlane32_swap_b32_e32 v94, v95
	v_max_f32_e32 v94, v94, v95
	v_cmp_lt_f32_e32 vcc, s51, v94
	s_cmp_lg_u64 vcc, 0
	v_add_f32_e32 v224, v224, v110
	s_cselect_b64 s[4:5], -1, 0
	s_cbranch_vccnz .LBB0_718

.LBB0_722:
	v_add_u32_e32 v186, s0, v207
	ds_read_b64_tr_b16 v[178:179], v186 offset:24576
	ds_read_b64_tr_b16 v[180:181], v186 offset:25088
	s_waitcnt lgkmcnt(9)
	v_mfma_f32_32x32x16_bf16 v[98:113], v[174:177], v[142:145], v[34:49]
	v_add_f32_e32 v82, v66, v67
	v_add_f32_e32 v82, v68, v82
	v_add_f32_e32 v82, v69, v82
	v_add_f32_e32 v82, v70, v82
	v_add_f32_e32 v82, v71, v82
	v_cvt_pk_bf16_f32 v134, v66, v67
	v_cvt_pk_bf16_f32 v135, v68, v69
	ds_read_b64_tr_b16 v[174:175], v186 offset:28672
	ds_read_b64_tr_b16 v[176:177], v186 offset:29184
	v_add_f32_e32 v66, v72, v82
	s_waitcnt lgkmcnt(10)
	v_mfma_f32_32x32x16_bf16 v[82:97], v[170:173], v[142:145], v[34:49]
	v_add_f32_e32 v66, v73, v66
	v_add_f32_e32 v66, v74, v66
	v_add_f32_e32 v114, v75, v66
	v_cvt_pk_bf16_f32 v136, v70, v71
	v_cvt_pk_bf16_f32 v137, v72, v73
	ds_read_b64_tr_b16 v[66:67], v186 offset:25600
	ds_read_b64_tr_b16 v[68:69], v186 offset:26112
	s_waitcnt lgkmcnt(11)
	v_mfma_f32_32x32x16_bf16 v[98:113], v[166:169], v[138:141], v[98:113]
	v_add_f32_e32 v70, v76, v114
	v_add_f32_e32 v70, v77, v70
	v_add_f32_e32 v70, v78, v70
	v_add_f32_e32 v114, v79, v70
	v_cvt_pk_bf16_f32 v126, v74, v75
	v_cvt_pk_bf16_f32 v127, v76, v77
	ds_read_b64_tr_b16 v[70:71], v186 offset:29696
	ds_read_b64_tr_b16 v[72:73], v186 offset:30208
	s_waitcnt lgkmcnt(12)
	v_mfma_f32_32x32x16_bf16 v[82:97], v[162:165], v[138:141], v[82:97]
	v_add_f32_e32 v74, v80, v114
	v_add_f32_e32 v74, v81, v74
	v_add_f32_e32 v74, v50, v74
	v_add_f32_e32 v114, v51, v74
	v_cvt_pk_bf16_f32 v128, v78, v79
	v_cvt_pk_bf16_f32 v129, v80, v81
	ds_read_b64_tr_b16 v[74:75], v186 offset:26624
	ds_read_b64_tr_b16 v[76:77], v186 offset:27136
	s_waitcnt lgkmcnt(13)
	v_mfma_f32_32x32x16_bf16 v[98:113], v[158:161], v[130:133], v[98:113]
	v_add_f32_e32 v78, v52, v114
	v_add_f32_e32 v78, v53, v78
	v_add_f32_e32 v78, v54, v78
	v_add_f32_e32 v78, v55, v78
	v_cvt_pk_bf16_f32 v118, v50, v51
	v_cvt_pk_bf16_f32 v119, v52, v53
	ds_read_b64_tr_b16 v[50:51], v186 offset:30720
	ds_read_b64_tr_b16 v[52:53], v186 offset:31232
	s_waitcnt lgkmcnt(14)
	v_mfma_f32_32x32x16_bf16 v[82:97], v[154:157], v[130:133], v[82:97]
	v_add_f32_e32 v78, v56, v78
	v_add_f32_e32 v78, v57, v78
	v_add_f32_e32 v78, v58, v78
	v_add_f32_e32 v78, v59, v78
	v_cvt_pk_bf16_f32 v120, v54, v55
	v_cvt_pk_bf16_f32 v121, v56, v57
	ds_read_b64_tr_b16 v[54:55], v186 offset:27648
	ds_read_b64_tr_b16 v[56:57], v186 offset:28160
	s_waitcnt lgkmcnt(14)
	v_mfma_f32_32x32x16_bf16 v[98:113], v[150:153], v[122:125], v[98:113]
	v_add_f32_e32 v78, v60, v78
	v_add_f32_e32 v78, v61, v78
	v_add_f32_e32 v78, v62, v78
	v_add_f32_e32 v78, v63, v78
	v_cvt_pk_bf16_f32 v114, v58, v59
	v_cvt_pk_bf16_f32 v115, v60, v61
	ds_read_b64_tr_b16 v[58:59], v186 offset:31744
	ds_read_b64_tr_b16 v[60:61], v186 offset:32256
	v_mfma_f32_32x32x16_bf16 v[82:97], v[146:149], v[122:125], v[82:97]
	v_add_f32_e32 v78, v64, v78
	v_add_f32_e32 v78, v65, v78
	v_cvt_pk_bf16_f32 v116, v62, v63
	v_cvt_pk_bf16_f32 v117, v64, v65
	s_cmpk_gt_u32 s21, 0x80
	s_cselect_b64 s[0:1], -1, 0
	s_and_b64 vcc, exec, s[0:1]
	s_cbranch_vccnz .LBB0_724
	s_sub_i32 s4, s20, 64
	v_mad_i64_i32 v[62:63], s[4:5], s4, v217, v[192:193]
	s_add_i32 s4, s23, s18
	s_mov_b32 m0, s4
	s_nop 0
	global_load_lds_dwordx4 v[62:63], off
.LBB0_724:
	v_max_f32_e32 v62, v98, v99
	v_max3_f32 v63, v100, v101, v83
	v_max3_f32 v62, v62, v82, v84
	v_max3_f32 v62, v62, v85, v102
	v_max3_f32 v63, v63, v104, v105
	v_max3_f32 v62, v62, v103, v86
	v_max3_f32 v63, v63, v88, v89
	v_max3_f32 v62, v62, v87, v106
	v_max3_f32 v63, v63, v108, v109
	v_max3_f32 v62, v62, v107, v90
	v_max3_f32 v63, v63, v92, v93
	v_max3_f32 v62, v62, v91, v110
	v_max3_f32 v63, v63, v112, v113
	v_max3_f32 v62, v62, v111, v94
	v_max3_f32 v63, v63, v96, v97
	v_max3_f32 v62, v62, v95, v63
	v_mov_b32_e32 v63, v62
	s_nop 1
	v_permlane32_swap_b32_e32 v62, v63
	v_max_f32_e32 v62, v62, v63
	s_add_i32 s4, s22, s19
	s_mov_b32 m0, s4
	s_nop 0
	global_load_lds_dwordx4 v[194:195], off
	v_cmp_lt_f32_e32 vcc, s51, v62
	s_cmp_lg_u64 vcc, 0
	v_add_f32_e32 v196, v224, v78
	s_cselect_b64 s[4:5], -1, 0
	s_cbranch_vccnz .LBB0_750

.LBB0_733:
	v_add_u32_e32 v186, s23, v207
	ds_read_b64_tr_b16 v[154:155], v186 offset:24576
	ds_read_b64_tr_b16 v[156:157], v186 offset:25088
	s_waitcnt lgkmcnt(9)
	v_mfma_f32_32x32x16_bf16 v[66:81], v[62:65], v[142:145], v[34:49]
	v_add_f32_e32 v50, v98, v99
	v_add_f32_e32 v50, v100, v50
	v_add_f32_e32 v50, v101, v50
	v_add_f32_e32 v50, v102, v50
	v_add_f32_e32 v50, v103, v50
	v_cvt_pk_bf16_f32 v134, v98, v99
	v_cvt_pk_bf16_f32 v135, v100, v101
	ds_read_b64_tr_b16 v[150:151], v186 offset:28672
	ds_read_b64_tr_b16 v[152:153], v186 offset:29184
	v_add_f32_e32 v50, v104, v50
	v_add_f32_e32 v50, v105, v50
	v_add_f32_e32 v50, v106, v50
	v_add_f32_e32 v114, v107, v50
	s_waitcnt lgkmcnt(10)
	v_mfma_f32_32x32x16_bf16 v[50:65], v[174:177], v[142:145], v[34:49]
	v_cvt_pk_bf16_f32 v136, v102, v103
	v_cvt_pk_bf16_f32 v137, v104, v105
	ds_read_b64_tr_b16 v[98:99], v186 offset:25600
	ds_read_b64_tr_b16 v[100:101], v186 offset:26112
	s_waitcnt lgkmcnt(11)
	v_mfma_f32_32x32x16_bf16 v[66:81], v[178:181], v[138:141], v[66:81]
	v_add_f32_e32 v102, v108, v114
	v_add_f32_e32 v102, v109, v102
	v_add_f32_e32 v102, v110, v102
	v_add_f32_e32 v114, v111, v102
	v_cvt_pk_bf16_f32 v126, v106, v107
	v_cvt_pk_bf16_f32 v127, v108, v109
	ds_read_b64_tr_b16 v[102:103], v186 offset:29696
	ds_read_b64_tr_b16 v[104:105], v186 offset:30208
	s_waitcnt lgkmcnt(12)
	v_mfma_f32_32x32x16_bf16 v[50:65], v[170:173], v[138:141], v[50:65]
	v_add_f32_e32 v106, v112, v114
	v_add_f32_e32 v106, v113, v106
	v_add_f32_e32 v106, v82, v106
	v_add_f32_e32 v114, v83, v106
	v_cvt_pk_bf16_f32 v128, v110, v111
	v_cvt_pk_bf16_f32 v129, v112, v113
	ds_read_b64_tr_b16 v[106:107], v186 offset:26624
	ds_read_b64_tr_b16 v[108:109], v186 offset:27136
	s_waitcnt lgkmcnt(13)
	v_mfma_f32_32x32x16_bf16 v[66:81], v[166:169], v[130:133], v[66:81]
	v_add_f32_e32 v110, v84, v114
	v_add_f32_e32 v110, v85, v110
	v_add_f32_e32 v110, v86, v110
	v_add_f32_e32 v110, v87, v110
	v_cvt_pk_bf16_f32 v118, v82, v83
	v_cvt_pk_bf16_f32 v119, v84, v85
	ds_read_b64_tr_b16 v[82:83], v186 offset:30720
	ds_read_b64_tr_b16 v[84:85], v186 offset:31232
	s_waitcnt lgkmcnt(14)
	v_mfma_f32_32x32x16_bf16 v[50:65], v[162:165], v[130:133], v[50:65]
	v_add_f32_e32 v110, v88, v110
	v_add_f32_e32 v110, v89, v110
	v_add_f32_e32 v110, v90, v110
	v_add_f32_e32 v110, v91, v110
	v_cvt_pk_bf16_f32 v120, v86, v87
	v_cvt_pk_bf16_f32 v121, v88, v89
	ds_read_b64_tr_b16 v[86:87], v186 offset:27648
	ds_read_b64_tr_b16 v[88:89], v186 offset:28160
	s_waitcnt lgkmcnt(14)
	v_mfma_f32_32x32x16_bf16 v[66:81], v[158:161], v[122:125], v[66:81]
	v_add_f32_e32 v110, v92, v110
	v_add_f32_e32 v110, v93, v110
	v_add_f32_e32 v110, v94, v110
	v_add_f32_e32 v110, v95, v110
	v_cvt_pk_bf16_f32 v114, v90, v91
	v_cvt_pk_bf16_f32 v115, v92, v93
	ds_read_b64_tr_b16 v[90:91], v186 offset:31744
	ds_read_b64_tr_b16 v[92:93], v186 offset:32256
	v_mfma_f32_32x32x16_bf16 v[50:65], v[146:149], v[122:125], v[50:65]
	v_add_f32_e32 v110, v96, v110
	v_add_f32_e32 v110, v97, v110
	v_cvt_pk_bf16_f32 v116, v94, v95
	v_cvt_pk_bf16_f32 v117, v96, v97
	s_cmpk_gt_u32 s21, 0x7f
	s_cselect_b64 s[4:5], -1, 0
	s_and_b64 vcc, exec, s[4:5]
	s_cbranch_vccnz .LBB0_735
	v_mad_i64_i32 v[94:95], s[6:7], s20, v217, v[192:193]
	s_add_i32 s6, s22, s18
	s_mov_b32 m0, s6
	s_nop 0
	global_load_lds_dwordx4 v[94:95], off
.LBB0_735:
	s_add_i32 s6, s22, 0x2000
	s_cmpk_lg_i32 s22, 0x4000
	s_cselect_b32 s23, s6, 0
	v_lshl_add_u64 v[94:95], v[194:195], 0, s[30:31]
	s_add_i32 s6, s23, s19
	s_mov_b32 m0, s6
	s_nop 0
	global_load_lds_dwordx4 v[94:95], off
	v_max_f32_e32 v94, v66, v67
	v_max3_f32 v95, v68, v69, v51
	v_max3_f32 v94, v94, v50, v52
	v_max3_f32 v94, v94, v53, v70
	v_max3_f32 v95, v95, v72, v73
	v_max3_f32 v94, v94, v71, v54
	v_max3_f32 v95, v95, v56, v57
	v_max3_f32 v94, v94, v55, v74
	v_max3_f32 v95, v95, v76, v77
	v_max3_f32 v94, v94, v75, v58
	v_max3_f32 v95, v95, v60, v61
	v_max3_f32 v94, v94, v59, v78
	v_max3_f32 v95, v95, v80, v81
	v_max3_f32 v94, v94, v79, v62
	v_max3_f32 v95, v95, v64, v65
	v_max3_f32 v94, v94, v63, v95
	v_mov_b32_e32 v95, v94
	s_nop 1
	v_permlane32_swap_b32_e32 v94, v95
	v_max_f32_e32 v94, v94, v95
	v_cmp_lt_f32_e32 vcc, s51, v94
	s_cmp_lg_u64 vcc, 0
	v_add_f32_e32 v224, v196, v110
	s_cselect_b64 s[6:7], -1, 0
	s_cbranch_vccnz .LBB0_753

.LBB0_756:
	ds_read_b64_tr_b16 v[98:99], v207 offset:32768
	ds_read_b64_tr_b16 v[100:101], v207 offset:33280
	v_add_f32_e32 v82, v66, v67
	v_add_f32_e32 v82, v68, v82
	v_add_f32_e32 v82, v69, v82
	v_add_f32_e32 v82, v70, v82
	v_add_f32_e32 v102, v71, v82
	s_waitcnt lgkmcnt(9)
	v_mfma_f32_32x32x16_bf16 v[82:97], v[174:177], v[142:145], v[34:49]
	v_cvt_pk_bf16_f32 v134, v66, v67
	v_cvt_pk_bf16_f32 v135, v68, v69
	ds_read_b64_tr_b16 v[66:67], v207 offset:36864
	ds_read_b64_tr_b16 v[68:69], v207 offset:37376
	s_waitcnt lgkmcnt(10)
	v_mfma_f32_32x32x16_bf16 v[34:49], v[170:173], v[142:145], v[34:49]
	v_add_f32_e32 v102, v72, v102
	v_add_f32_e32 v102, v73, v102
	v_add_f32_e32 v102, v74, v102
	v_add_f32_e32 v102, v75, v102
	v_cvt_pk_bf16_f32 v136, v70, v71
	v_cvt_pk_bf16_f32 v137, v72, v73
	ds_read_b64_tr_b16 v[70:71], v207 offset:33792
	ds_read_b64_tr_b16 v[72:73], v207 offset:34304
	s_waitcnt lgkmcnt(11)
	v_mfma_f32_32x32x16_bf16 v[82:97], v[166:169], v[138:141], v[82:97]
	v_add_f32_e32 v102, v76, v102
	v_add_f32_e32 v102, v77, v102
	v_add_f32_e32 v102, v78, v102
	v_add_f32_e32 v102, v79, v102
	v_cvt_pk_bf16_f32 v126, v74, v75
	v_cvt_pk_bf16_f32 v127, v76, v77
	ds_read_b64_tr_b16 v[74:75], v207 offset:37888
	ds_read_b64_tr_b16 v[76:77], v207 offset:38400
	s_waitcnt lgkmcnt(12)
	v_mfma_f32_32x32x16_bf16 v[34:49], v[162:165], v[138:141], v[34:49]
	v_add_f32_e32 v102, v80, v102
	v_add_f32_e32 v102, v81, v102
	v_add_f32_e32 v102, v50, v102
	v_add_f32_e32 v102, v51, v102
	v_cvt_pk_bf16_f32 v128, v78, v79
	v_cvt_pk_bf16_f32 v129, v80, v81
	ds_read_b64_tr_b16 v[78:79], v207 offset:34816
	ds_read_b64_tr_b16 v[80:81], v207 offset:35328
	s_waitcnt lgkmcnt(13)
	v_mfma_f32_32x32x16_bf16 v[82:97], v[158:161], v[130:133], v[82:97]
	v_add_f32_e32 v102, v52, v102
	v_add_f32_e32 v102, v53, v102
	v_add_f32_e32 v102, v54, v102
	v_add_f32_e32 v106, v55, v102
	v_cvt_pk_bf16_f32 v118, v50, v51
	v_cvt_pk_bf16_f32 v119, v52, v53
	ds_read_b64_tr_b16 v[102:103], v207 offset:38912
	ds_read_b64_tr_b16 v[104:105], v207 offset:39424
	s_waitcnt lgkmcnt(14)
	v_mfma_f32_32x32x16_bf16 v[34:49], v[154:157], v[130:133], v[34:49]
	v_add_f32_e32 v50, v56, v106
	v_add_f32_e32 v50, v57, v50
	v_add_f32_e32 v50, v58, v50
	v_add_f32_e32 v50, v59, v50
	v_cvt_pk_bf16_f32 v120, v54, v55
	v_cvt_pk_bf16_f32 v121, v56, v57
	ds_read_b64_tr_b16 v[106:107], v207 offset:35840
	ds_read_b64_tr_b16 v[108:109], v207 offset:36352
	s_waitcnt lgkmcnt(14)
	v_mfma_f32_32x32x16_bf16 v[82:97], v[150:153], v[122:125], v[82:97]
	v_add_f32_e32 v50, v60, v50
	v_add_f32_e32 v50, v61, v50
	v_add_f32_e32 v50, v62, v50
	v_add_f32_e32 v50, v63, v50
	v_cvt_pk_bf16_f32 v114, v58, v59
	v_cvt_pk_bf16_f32 v115, v60, v61
	ds_read_b64_tr_b16 v[110:111], v207 offset:39936
	ds_read_b64_tr_b16 v[112:113], v207 offset:40448
	v_mfma_f32_32x32x16_bf16 v[34:49], v[146:149], v[122:125], v[34:49]
	v_add_f32_e32 v50, v64, v50
	v_add_f32_e32 v50, v65, v50
	v_cvt_pk_bf16_f32 v116, v62, v63
	v_cvt_pk_bf16_f32 v117, v64, v65
	v_max_f32_e32 v51, v82, v83
	s_nop 3
	v_max3_f32 v52, v84, v85, v35
	v_max3_f32 v51, v51, v34, v36
	v_max3_f32 v51, v51, v37, v86
	v_max3_f32 v52, v52, v88, v89
	v_max3_f32 v51, v51, v87, v38
	v_max3_f32 v52, v52, v40, v41
	v_max3_f32 v51, v51, v39, v90
	v_max3_f32 v52, v52, v92, v93
	v_max3_f32 v51, v51, v91, v42
	v_max3_f32 v52, v52, v44, v45
	v_max3_f32 v51, v51, v43, v94
	v_max3_f32 v52, v52, v96, v97
	v_max3_f32 v51, v51, v95, v46
	v_max3_f32 v52, v52, v48, v49
	v_add_f32_e32 v122, v224, v50
	v_max3_f32 v50, v51, v47, v52
	v_mov_b32_e32 v51, v50
	s_nop 1
	v_permlane32_swap_b32_e32 v50, v51
	v_max_f32_e32 v50, v50, v51
	v_cmp_lt_f32_e32 vcc, s51, v50
	s_cmp_lg_u64 vcc, 0
	s_cselect_b64 s[0:1], -1, 0
	s_cbranch_vccnz .LBB0_761

.LBB0_891:
	s_sext_i32_i8 s11, s3
	s_lshl_b32 s12, s11, 8
	s_add_i32 s18, s12, 0x4000
	s_add_i32 s3, s9, 0x280
	s_and_b64 s[0:1], exec, s[0:1]
	s_cselect_b32 s0, s9, s3
	s_mul_i32 s3, s18, 0xe00
	v_readlane_b32 s14, v254, 35
	s_mul_hi_u32 s1, s18, 0xe00
	v_readlane_b32 s15, v254, 36
	s_add_u32 s3, s14, s3
	s_addc_u32 s5, s15, s1
	s_ashr_i32 s1, s0, 31
	s_lshl_b64 s[0:1], s[0:1], 1
	s_add_u32 s10, s3, s0
	s_mov_b32 s3, s19
	s_addc_u32 s13, s5, s1
	s_lshl_b64 s[0:1], s[2:3], 1
	s_add_u32 s0, s14, s0
	s_mov_b32 s5, s19
	s_addc_u32 s1, s15, s1
	s_lshl_b64 s[2:3], s[4:5], 1
	s_add_u32 s14, s14, s2
	v_mov_b32_e32 v36, v191
	s_addc_u32 s15, s15, s3
	v_mov_b32_e32 v4, v1
	v_readfirstlane_b32 s3, v36
	v_and_b32_e32 v189, 63, v36
	s_ashr_i32 s7, s3, 6
	s_lshl_b32 s2, s7, 5
	s_mul_i32 s4, s7, 0x1c000
	v_mul_u32_u24_e32 v0, 0x700, v189
	s_mul_hi_i32 s5, s2, 0xe00
	s_add_u32 s16, s10, s4
	v_lshlrev_b32_e32 v0, 1, v0
	s_addc_u32 s17, s13, s5
	v_lshl_add_u64 v[2:3], s[0:1], 0, v[0:1]
	s_lshl_b32 s0, s7, 3
	s_ashr_i32 s1, s0, 31
	v_lshl_add_u64 v[34:35], s[0:1], 1, v[2:3]
	s_lshl_b32 s0, s7, 4
	v_bfe_u32 v0, v36, 2, 4
	v_and_or_b32 v0, s0, 48, v0
	v_mul_u32_u24_e32 v0, 0x700, v0
	s_ashr_i32 s0, s3, 3
	v_lshlrev_b32_e32 v0, 1, v0
	s_andn2_b32 s0, s0, 31
	v_lshl_add_u64 v[2:3], s[14:15], 0, v[0:1]
	s_ashr_i32 s1, s0, 31
	s_and_b32 s4, s3, 0x3fffffc0
	v_lshl_add_u64 v[2:3], s[0:1], 1, v[2:3]
	v_lshlrev_b32_e32 v194, 3, v36
	s_lshl_b32 s0, s7, 10
	v_and_b32_e32 v197, 24, v194
	s_cmp_lg_u32 0, -1
	v_lshlrev_b32_e32 v0, 1, v197
	s_cselect_b32 s1, 0, 0
	v_and_b32_e32 v195, 31, v36
	v_lshl_add_u64 v[38:39], v[2:3], 0, v[0:1]
	s_add_i32 s0, s1, s0
	v_mad_u64_u32 v[2:3], s[14:15], s18, v217, v[34:35]
	s_mov_b32 m0, s0
	s_nop 0
	global_load_lds_dwordx4 v[2:3], off
	s_add_i32 s3, s0, 0x6000
	v_mad_u64_u32 v[2:3], s[14:15], s18, v217, v[38:39]
	s_mov_b32 m0, s3
	s_nop 0
	global_load_lds_dwordx4 v[2:3], off
	v_mul_u32_u24_e32 v0, 0x700, v195
	v_bfe_u32 v196, v36, 5, 1
	s_add_i32 s1, s12, 0x4040
	v_lshlrev_b32_e32 v0, 1, v0
	v_mad_u64_u32 v[2:3], s[14:15], s1, v217, v[34:35]
	s_add_i32 s5, s0, 0x2000
	s_mov_b32 m0, s5
	s_nop 0
	global_load_lds_dwordx4 v[2:3], off
	v_lshl_or_b32 v0, v196, 4, v0
	global_load_dwordx4 v[142:145], v0, s[16:17]
	global_load_dwordx4 v[138:141], v0, s[16:17] offset:32
	global_load_dwordx4 v[130:133], v0, s[16:17] offset:64
	global_load_dwordx4 v[114:117], v0, s[16:17] offset:96
	v_lshlrev_b32_e32 v2, 4, v195
	v_lshl_add_u32 v0, v196, 10, 0
	v_add_u32_e32 v203, v0, v2
	v_mov_b32_e32 v2, v1
	v_mov_b32_e32 v3, v1
	v_mov_b32_e32 v5, v1
	v_mov_b32_e32 v6, v1
	v_mov_b32_e32 v7, v1
	v_mov_b32_e32 v8, v1
	v_mov_b32_e32 v9, v1
	v_mov_b32_e32 v10, v1
	v_mov_b32_e32 v11, v1
	v_mov_b32_e32 v12, v1
	v_mov_b32_e32 v13, v1
	v_mov_b32_e32 v14, v1
	v_mov_b32_e32 v15, v1
	v_mov_b32_e32 v0, v1
	v_mov_b64_e32 v[16:17], v[14:15]
	v_mov_b64_e32 v[14:15], v[12:13]
	v_mov_b64_e32 v[12:13], v[10:11]
	v_mov_b64_e32 v[10:11], v[8:9]
	v_mov_b64_e32 v[8:9], v[6:7]
	v_mov_b64_e32 v[6:7], v[4:5]
	v_mov_b64_e32 v[4:5], v[2:3]
	v_mov_b64_e32 v[2:3], v[0:1]
	s_add_i32 s5, s12, 0x4080
	v_mad_u64_u32 v[18:19], s[14:15], s5, v217, v[34:35]
	s_add_i32 s5, s0, 0x4000
	s_mov_b32 m0, s5
	s_nop 0
	global_load_lds_dwordx4 v[18:19], off
	s_waitcnt vmcnt(3) lgkmcnt(0)
	s_barrier
	ds_read_b128 v[40:43], v203
	ds_read_b128 v[44:47], v203 offset:512
	s_waitcnt vmcnt(3) lgkmcnt(1)
	v_mfma_f32_32x32x16_bf16 v[18:33], v[40:43], v[142:145], v[2:17]
	s_lshl_b32 s4, s4, 2
	s_addk_i32 s12, 0x40c0
	s_add_i32 s10, s4, 0
	v_lshlrev_b32_e32 v0, 1, v36
	v_lshlrev_b32_e32 v36, 4, v36
	v_and_b32_e32 v0, 32, v0
	v_and_b32_e32 v36, 0xc0, v36
	s_waitcnt lgkmcnt(0)
	v_mfma_f32_32x32x16_bf16 v[2:17], v[44:47], v[142:145], v[2:17]
	ds_read_b128 v[40:43], v203 offset:2048
	ds_read_b128 v[44:47], v203 offset:2560
	v_lshl_or_b32 v198, v196, 8, v36
	v_add3_u32 v36, 0, v0, v197
	v_add_u32_e32 v202, v36, v198
	v_cmp_gt_u32_e64 s[40:41], 32, v189
	v_lshl_add_u32 v199, v195, 2, s10
	s_waitcnt vmcnt(2) lgkmcnt(1)
	v_mfma_f32_32x32x16_bf16 v[18:33], v[40:43], v[138:141], v[18:33]
	s_waitcnt lgkmcnt(0)
	v_mfma_f32_32x32x16_bf16 v[2:17], v[44:47], v[138:141], v[2:17]
	ds_read_b128 v[40:43], v203 offset:4096
	ds_read_b128 v[44:47], v203 offset:4608
	s_waitcnt vmcnt(1) lgkmcnt(1)
	v_mfma_f32_32x32x16_bf16 v[18:33], v[40:43], v[130:133], v[18:33]
	s_waitcnt lgkmcnt(0)
	v_mfma_f32_32x32x16_bf16 v[2:17], v[44:47], v[130:133], v[2:17]
	ds_read_b128 v[40:43], v203 offset:6144
	ds_read_b128 v[44:47], v203 offset:6656
	s_waitcnt vmcnt(0) lgkmcnt(1)
	v_mfma_f32_32x32x16_bf16 v[18:33], v[40:43], v[114:117], v[18:33]
	s_waitcnt lgkmcnt(0)
	v_mfma_f32_32x32x16_bf16 v[2:17], v[44:47], v[114:117], v[2:17]
	s_nop 15
	s_nop 7
	s_nop 0
	v_max3_f32 v37, v18, v19, v2
	v_max3_f32 v40, v20, v21, v3
	s_nop 0
	v_max3_f32 v37, v37, v4, v5
	v_max3_f32 v40, v40, v24, v25
	s_nop 0
	v_max3_f32 v37, v37, v22, v23
	v_max3_f32 v40, v40, v8, v9
	s_nop 0
	v_max3_f32 v37, v37, v6, v7
	v_max3_f32 v40, v40, v28, v29
	s_nop 0
	v_max3_f32 v37, v37, v26, v27
	v_max3_f32 v40, v40, v12, v13
	s_nop 0
	v_max3_f32 v37, v37, v10, v11
	v_max3_f32 v40, v40, v32, v33
	s_nop 0
	v_max3_f32 v37, v37, v30, v31
	v_max3_f32 v40, v40, v16, v17
	s_nop 0
	v_max3_f32 v37, v37, v14, v15
	s_nop 0
	v_max_f32_e32 v37, v37, v40
	s_nop 0
	v_mov_b32_e32 v40, v37
	s_nop 1
	v_permlane32_swap_b32_e32 v37, v40
	v_max_f32_e32 v37, v37, v40
	s_nop 0
	v_add_f32_e32 v200, v1, v37
	v_sub_f32_e32 v40, v2, v37
	v_sub_f32_e32 v18, v18, v37
	v_sub_f32_e32 v19, v19, v37
	v_sub_f32_e32 v41, v3, v37
	v_sub_f32_e32 v20, v20, v37
	s_nop 0
	v_xor_b32_e32 v2, 0x80000000, v200
	v_sub_f32_e32 v42, v4, v37
	v_sub_f32_e32 v21, v21, v37
	v_sub_f32_e32 v43, v5, v37
	v_sub_f32_e32 v22, v22, v37
	v_sub_f32_e32 v44, v6, v37
	v_sub_f32_e32 v23, v23, v37
	v_sub_f32_e32 v45, v7, v37
	v_sub_f32_e32 v24, v24, v37
	v_sub_f32_e32 v46, v8, v37
	v_sub_f32_e32 v25, v25, v37
	v_sub_f32_e32 v47, v9, v37
	v_sub_f32_e32 v26, v26, v37
	v_sub_f32_e32 v48, v10, v37
	v_sub_f32_e32 v27, v27, v37
	v_sub_f32_e32 v49, v11, v37
	v_sub_f32_e32 v28, v28, v37
	v_sub_f32_e32 v50, v12, v37
	v_sub_f32_e32 v29, v29, v37
	v_sub_f32_e32 v51, v13, v37
	v_sub_f32_e32 v30, v30, v37
	v_sub_f32_e32 v52, v14, v37
	v_sub_f32_e32 v31, v31, v37
	v_sub_f32_e32 v53, v15, v37
	v_sub_f32_e32 v32, v32, v37
	v_sub_f32_e32 v54, v16, v37
	v_sub_f32_e32 v33, v33, v37
	v_sub_f32_e32 v37, v17, v37
	v_mov_b32_e32 v3, v2
	v_mov_b32_e32 v4, v2
	v_mov_b32_e32 v5, v2
	v_mov_b32_e32 v6, v2
	v_mov_b32_e32 v7, v2
	v_mov_b32_e32 v8, v2
	v_mov_b32_e32 v9, v2
	v_mov_b32_e32 v10, v2
	v_mov_b32_e32 v11, v2
	v_mov_b32_e32 v12, v2
	v_mov_b32_e32 v13, v2
	v_mov_b32_e32 v14, v2
	v_mov_b32_e32 v15, v2
	v_mov_b32_e32 v16, v2
	v_mov_b32_e32 v17, v2
	s_waitcnt vmcnt(0) lgkmcnt(0)
	s_barrier
	v_exp_f32_e32 v55, v18
	v_exp_f32_e32 v56, v19
	v_mad_u64_u32 v[18:19], s[4:5], s12, v217, v[34:35]
	s_mov_b32 m0, s0
	s_nop 0
	global_load_lds_dwordx4 v[18:19], off
	v_exp_f32_e32 v59, v22
	v_mad_u64_u32 v[18:19], s[4:5], s1, v217, v[38:39]
	s_add_i32 s1, s0, 0x8000
	s_mov_b32 m0, s1
	s_nop 0
	global_load_lds_dwordx4 v[18:19], off
	v_exp_f32_e32 v60, v23
	v_exp_f32_e32 v61, v24
	v_exp_f32_e32 v62, v25
	v_exp_f32_e32 v63, v26
	v_exp_f32_e32 v64, v27
	v_exp_f32_e32 v65, v28
	v_exp_f32_e32 v94, v29
	v_exp_f32_e32 v95, v30
	v_exp_f32_e32 v96, v31
	v_exp_f32_e32 v97, v32
	v_exp_f32_e32 v126, v33
	v_exp_f32_e32 v127, v40
	v_exp_f32_e32 v128, v41
	v_exp_f32_e32 v129, v42
	v_exp_f32_e32 v134, v43
	v_exp_f32_e32 v135, v44
	v_exp_f32_e32 v136, v45
	v_exp_f32_e32 v137, v46
	v_exp_f32_e32 v146, v47
	ds_read_b128 v[22:25], v203 offset:8192
	ds_read_b128 v[26:29], v203 offset:8704
	ds_read_b128 v[30:33], v203 offset:10240
	ds_read_b128 v[40:43], v203 offset:10752
	ds_read_b128 v[44:47], v203 offset:12288
	ds_read_b128 v[82:85], v203 offset:12800
	ds_read_b128 v[86:89], v203 offset:14336
	ds_read_b128 v[90:93], v203 offset:14848
	v_exp_f32_e32 v57, v20
	v_exp_f32_e32 v58, v21
	s_waitcnt vmcnt(2) lgkmcnt(0)
	s_barrier
	v_exp_f32_e32 v48, v48
	v_exp_f32_e32 v49, v49
	v_exp_f32_e32 v147, v50
	v_exp_f32_e32 v148, v51
	v_exp_f32_e32 v149, v52
	v_exp_f32_e32 v150, v53
	v_exp_f32_e32 v151, v54
	v_exp_f32_e32 v152, v37
	ds_read_b64_tr_b16 v[18:19], v202 offset:24576
	ds_read_b64_tr_b16 v[20:21], v202 offset:25088
	s_waitcnt lgkmcnt(9)
	v_mfma_f32_32x32x16_bf16 v[98:113], v[22:25], v[142:145], v[2:17]
	v_add_f32_e32 v34, v55, v56
	v_add_f32_e32 v34, v34, v57
	v_add_f32_e32 v34, v34, v58
	v_add_f32_e32 v34, v34, v59
	v_add_f32_e32 v50, v34, v60
	v_cvt_pk_bf16_f32 v122, v55, v56
	v_cvt_pk_bf16_f32 v123, v57, v58
	ds_read_b64_tr_b16 v[34:35], v202 offset:28672
	ds_read_b64_tr_b16 v[36:37], v202 offset:29184
	s_waitcnt lgkmcnt(10)
	v_mfma_f32_32x32x16_bf16 v[66:81], v[26:29], v[142:145], v[2:17]
	v_add_f32_e32 v22, v61, v50
	v_add_f32_e32 v22, v62, v22
	v_add_f32_e32 v22, v63, v22
	v_add_f32_e32 v22, v64, v22
	v_cvt_pk_bf16_f32 v124, v59, v60
	v_cvt_pk_bf16_f32 v125, v61, v62
	ds_read_b64_tr_b16 v[50:51], v202 offset:25600
	ds_read_b64_tr_b16 v[52:53], v202 offset:26112
	s_waitcnt lgkmcnt(11)
	v_mfma_f32_32x32x16_bf16 v[98:113], v[30:33], v[138:141], v[98:113]
	v_add_f32_e32 v22, v65, v22
	v_add_f32_e32 v22, v94, v22
	v_add_f32_e32 v22, v95, v22
	v_add_f32_e32 v22, v96, v22
	v_cvt_pk_bf16_f32 v118, v63, v64
	v_cvt_pk_bf16_f32 v119, v65, v94
	ds_read_b64_tr_b16 v[54:55], v202 offset:29696
	ds_read_b64_tr_b16 v[56:57], v202 offset:30208
	s_waitcnt lgkmcnt(12)
	v_mfma_f32_32x32x16_bf16 v[66:81], v[40:43], v[138:141], v[66:81]
	v_add_f32_e32 v22, v97, v22
	v_add_f32_e32 v22, v126, v22
	v_add_f32_e32 v22, v127, v22
	v_add_f32_e32 v22, v128, v22
	v_cvt_pk_bf16_f32 v120, v95, v96
	v_cvt_pk_bf16_f32 v121, v97, v126
	ds_read_b64_tr_b16 v[58:59], v202 offset:26624
	ds_read_b64_tr_b16 v[60:61], v202 offset:27136
	s_waitcnt lgkmcnt(13)
	v_mfma_f32_32x32x16_bf16 v[98:113], v[44:47], v[130:133], v[98:113]
	v_add_f32_e32 v22, v129, v22
	v_add_f32_e32 v22, v134, v22
	v_add_f32_e32 v22, v135, v22
	v_add_f32_e32 v22, v136, v22
	v_cvt_pk_bf16_f32 v126, v127, v128
	v_cvt_pk_bf16_f32 v127, v129, v134
	ds_read_b64_tr_b16 v[62:63], v202 offset:30720
	ds_read_b64_tr_b16 v[64:65], v202 offset:31232
	s_waitcnt lgkmcnt(14)
	v_mfma_f32_32x32x16_bf16 v[66:81], v[82:85], v[130:133], v[66:81]
	v_add_f32_e32 v22, v137, v22
	v_add_f32_e32 v22, v146, v22
	v_add_f32_e32 v22, v48, v22
	v_add_f32_e32 v22, v49, v22
	v_cvt_pk_bf16_f32 v128, v135, v136
	v_cvt_pk_bf16_f32 v129, v137, v146
	ds_read_b64_tr_b16 v[82:83], v202 offset:27648
	ds_read_b64_tr_b16 v[84:85], v202 offset:28160
	s_waitcnt lgkmcnt(14)
	v_mfma_f32_32x32x16_bf16 v[98:113], v[86:89], v[114:117], v[98:113]
	v_add_f32_e32 v22, v147, v22
	v_add_f32_e32 v22, v148, v22
	v_add_f32_e32 v22, v149, v22
	v_add_f32_e32 v22, v150, v22
	v_cvt_pk_bf16_f32 v134, v48, v49
	v_cvt_pk_bf16_f32 v135, v147, v148
	ds_read_b64_tr_b16 v[86:87], v202 offset:31744
	ds_read_b64_tr_b16 v[88:89], v202 offset:32256
	v_mfma_f32_32x32x16_bf16 v[66:81], v[90:93], v[114:117], v[66:81]
	v_add_f32_e32 v22, v151, v22
	v_add_f32_e32 v22, v152, v22
	v_cvt_pk_bf16_f32 v136, v149, v150
	v_cvt_pk_bf16_f32 v137, v151, v152
	s_mul_i32 s4, s11, 0xe0000
	s_ashr_i32 s5, s4, 31
	v_lshl_add_u64 v[192:193], v[38:39], 0, s[4:5]
	s_mov_b64 s[4:5], 0x3870000
	v_add_f32_e32 v204, 0, v22
	v_lshl_add_u64 v[22:23], v[192:193], 0, s[4:5]
	s_add_i32 s0, s0, 0xa000
	s_mov_b32 m0, s0
	s_nop 0
	global_load_lds_dwordx4 v[22:23], off
	v_max_f32_e32 v22, v98, v99
	v_max3_f32 v23, v100, v101, v67
	v_max3_f32 v22, v22, v66, v68
	v_max3_f32 v22, v22, v69, v102
	v_max3_f32 v23, v23, v104, v105
	v_max3_f32 v22, v22, v103, v70
	v_max3_f32 v23, v23, v72, v73
	v_max3_f32 v22, v22, v71, v106
	v_max3_f32 v23, v23, v108, v109
	v_max3_f32 v22, v22, v107, v74
	v_max3_f32 v23, v23, v76, v77
	v_max3_f32 v22, v22, v75, v110
	v_max3_f32 v23, v23, v112, v113
	v_max3_f32 v22, v22, v111, v78
	v_max3_f32 v23, v23, v80, v81
	v_max3_f32 v22, v22, v79, v23
	v_mov_b32_e32 v23, v22
	s_nop 1
	v_permlane32_swap_b32_e32 v22, v23
	v_max_f32_e32 v22, v22, v23
	v_cmp_lt_f32_e32 vcc, s51, v22
	s_cmp_lg_u64 vcc, 0
	s_cselect_b64 s[0:1], -1, 0
	s_cbranch_vccnz .LBB0_902

.LBB0_894:
	ds_read_b64_tr_b16 v[150:151], v202 offset:32768
	ds_read_b64_tr_b16 v[152:153], v202 offset:33280
	s_waitcnt lgkmcnt(9)
	v_mfma_f32_32x32x16_bf16 v[82:97], v[146:149], v[142:145], v[2:17]
	v_add_f32_e32 v50, v98, v99
	v_add_f32_e32 v50, v100, v50
	v_add_f32_e32 v50, v101, v50
	v_add_f32_e32 v50, v102, v50
	v_add_f32_e32 v50, v103, v50
	v_cvt_pk_bf16_f32 v122, v98, v99
	v_cvt_pk_bf16_f32 v123, v100, v101
	ds_read_b64_tr_b16 v[146:147], v202 offset:36864
	ds_read_b64_tr_b16 v[148:149], v202 offset:37376
	v_add_f32_e32 v50, v104, v50
	v_add_f32_e32 v50, v105, v50
	v_add_f32_e32 v50, v106, v50
	v_add_f32_e32 v118, v107, v50
	s_waitcnt lgkmcnt(10)
	v_mfma_f32_32x32x16_bf16 v[50:65], v[174:177], v[142:145], v[2:17]
	v_cvt_pk_bf16_f32 v124, v102, v103
	v_cvt_pk_bf16_f32 v125, v104, v105
	ds_read_b64_tr_b16 v[98:99], v202 offset:33792
	ds_read_b64_tr_b16 v[100:101], v202 offset:34304
	s_waitcnt lgkmcnt(11)
	v_mfma_f32_32x32x16_bf16 v[82:97], v[178:181], v[138:141], v[82:97]
	v_add_f32_e32 v102, v108, v118
	v_add_f32_e32 v102, v109, v102
	v_add_f32_e32 v102, v110, v102
	v_add_f32_e32 v126, v111, v102
	v_cvt_pk_bf16_f32 v118, v106, v107
	v_cvt_pk_bf16_f32 v119, v108, v109
	ds_read_b64_tr_b16 v[102:103], v202 offset:37888
	ds_read_b64_tr_b16 v[104:105], v202 offset:38400
	s_waitcnt lgkmcnt(12)
	v_mfma_f32_32x32x16_bf16 v[50:65], v[170:173], v[138:141], v[50:65]
	v_add_f32_e32 v106, v112, v126
	v_add_f32_e32 v106, v113, v106
	v_add_f32_e32 v106, v66, v106
	v_add_f32_e32 v126, v67, v106
	v_cvt_pk_bf16_f32 v120, v110, v111
	v_cvt_pk_bf16_f32 v121, v112, v113
	ds_read_b64_tr_b16 v[106:107], v202 offset:34816
	ds_read_b64_tr_b16 v[108:109], v202 offset:35328
	s_waitcnt lgkmcnt(13)
	v_mfma_f32_32x32x16_bf16 v[82:97], v[166:169], v[130:133], v[82:97]
	v_add_f32_e32 v110, v68, v126
	v_add_f32_e32 v110, v69, v110
	v_add_f32_e32 v110, v70, v110
	v_add_f32_e32 v110, v71, v110
	v_cvt_pk_bf16_f32 v126, v66, v67
	v_cvt_pk_bf16_f32 v127, v68, v69
	ds_read_b64_tr_b16 v[66:67], v202 offset:38912
	ds_read_b64_tr_b16 v[68:69], v202 offset:39424
	s_waitcnt lgkmcnt(14)
	v_mfma_f32_32x32x16_bf16 v[50:65], v[162:165], v[130:133], v[50:65]
	v_add_f32_e32 v110, v72, v110
	v_add_f32_e32 v110, v73, v110
	v_add_f32_e32 v110, v74, v110
	v_add_f32_e32 v110, v75, v110
	v_cvt_pk_bf16_f32 v128, v70, v71
	v_cvt_pk_bf16_f32 v129, v72, v73
	ds_read_b64_tr_b16 v[70:71], v202 offset:35840
	ds_read_b64_tr_b16 v[72:73], v202 offset:36352
	s_waitcnt lgkmcnt(14)
	v_mfma_f32_32x32x16_bf16 v[82:97], v[158:161], v[114:117], v[82:97]
	v_add_f32_e32 v110, v76, v110
	v_add_f32_e32 v110, v77, v110
	v_add_f32_e32 v110, v78, v110
	v_add_f32_e32 v110, v79, v110
	v_cvt_pk_bf16_f32 v134, v74, v75
	v_cvt_pk_bf16_f32 v135, v76, v77
	ds_read_b64_tr_b16 v[74:75], v202 offset:39936
	ds_read_b64_tr_b16 v[76:77], v202 offset:40448
	v_mfma_f32_32x32x16_bf16 v[50:65], v[154:157], v[114:117], v[50:65]
	v_add_f32_e32 v110, v80, v110
	v_add_f32_e32 v110, v81, v110
	v_cvt_pk_bf16_f32 v136, v78, v79
	v_cvt_pk_bf16_f32 v137, v80, v81
	s_mov_b64 s[0:1], 0x38a8000
	v_lshl_add_u64 v[78:79], v[192:193], 0, s[0:1]
	s_mov_b32 m0, s3
	s_nop 0
	global_load_lds_dwordx4 v[78:79], off
	v_max_f32_e32 v78, v82, v83
	s_nop 1
	v_max3_f32 v79, v84, v85, v51
	v_max3_f32 v78, v78, v50, v52
	v_max3_f32 v78, v78, v53, v86
	v_max3_f32 v79, v79, v88, v89
	v_max3_f32 v78, v78, v87, v54
	v_max3_f32 v79, v79, v56, v57
	v_max3_f32 v78, v78, v55, v90
	v_max3_f32 v79, v79, v92, v93
	v_max3_f32 v78, v78, v91, v58
	v_max3_f32 v79, v79, v60, v61
	v_max3_f32 v78, v78, v59, v94
	v_max3_f32 v79, v79, v96, v97
	v_max3_f32 v78, v78, v95, v62
	v_max3_f32 v79, v79, v64, v65
	v_max3_f32 v78, v78, v63, v79
	v_mov_b32_e32 v79, v78
	s_nop 1
	v_permlane32_swap_b32_e32 v78, v79
	v_max_f32_e32 v78, v78, v79
	v_cmp_lt_f32_e32 vcc, s51, v78
	s_cmp_lg_u64 vcc, 0
	v_add_f32_e32 v170, v204, v110
	s_cselect_b64 s[0:1], -1, 0
	s_cbranch_vccnz .LBB0_905

.LBB0_897:
	ds_read_b64_tr_b16 v[98:99], v202 offset:40960
	ds_read_b64_tr_b16 v[100:101], v202 offset:41472
	v_add_f32_e32 v66, v82, v83
	v_add_f32_e32 v66, v84, v66
	v_add_f32_e32 v66, v85, v66
	v_add_f32_e32 v66, v86, v66
	v_add_f32_e32 v106, v87, v66
	s_waitcnt lgkmcnt(9)
	v_mfma_f32_32x32x16_bf16 v[66:81], v[166:169], v[142:145], v[2:17]
	v_cvt_pk_bf16_f32 v122, v82, v83
	v_cvt_pk_bf16_f32 v123, v84, v85
	ds_read_b64_tr_b16 v[82:83], v202 offset:45056
	ds_read_b64_tr_b16 v[84:85], v202 offset:45568
	s_waitcnt lgkmcnt(10)
	v_mfma_f32_32x32x16_bf16 v[2:17], v[162:165], v[142:145], v[2:17]
	v_add_f32_e32 v106, v88, v106
	v_add_f32_e32 v106, v89, v106
	v_add_f32_e32 v106, v90, v106
	v_add_f32_e32 v106, v91, v106
	v_cvt_pk_bf16_f32 v124, v86, v87
	v_cvt_pk_bf16_f32 v125, v88, v89
	ds_read_b64_tr_b16 v[86:87], v202 offset:41984
	ds_read_b64_tr_b16 v[88:89], v202 offset:42496
	s_waitcnt lgkmcnt(11)
	v_mfma_f32_32x32x16_bf16 v[66:81], v[158:161], v[138:141], v[66:81]
	v_add_f32_e32 v106, v92, v106
	v_add_f32_e32 v106, v93, v106
	v_add_f32_e32 v106, v94, v106
	v_add_f32_e32 v106, v95, v106
	v_cvt_pk_bf16_f32 v118, v90, v91
	v_cvt_pk_bf16_f32 v119, v92, v93
	ds_read_b64_tr_b16 v[90:91], v202 offset:46080
	ds_read_b64_tr_b16 v[92:93], v202 offset:46592
	s_waitcnt lgkmcnt(12)
	v_mfma_f32_32x32x16_bf16 v[2:17], v[154:157], v[138:141], v[2:17]
	v_add_f32_e32 v106, v96, v106
	v_add_f32_e32 v106, v97, v106
	v_add_f32_e32 v106, v50, v106
	v_add_f32_e32 v106, v51, v106
	v_cvt_pk_bf16_f32 v120, v94, v95
	v_cvt_pk_bf16_f32 v121, v96, v97
	ds_read_b64_tr_b16 v[94:95], v202 offset:43008
	ds_read_b64_tr_b16 v[96:97], v202 offset:43520
	s_waitcnt lgkmcnt(13)
	v_mfma_f32_32x32x16_bf16 v[66:81], v[102:105], v[130:133], v[66:81]
	v_add_f32_e32 v102, v52, v106
	v_add_f32_e32 v102, v53, v102
	v_add_f32_e32 v102, v54, v102
	v_add_f32_e32 v106, v55, v102
	v_cvt_pk_bf16_f32 v126, v50, v51
	v_cvt_pk_bf16_f32 v127, v52, v53
	ds_read_b64_tr_b16 v[102:103], v202 offset:47104
	ds_read_b64_tr_b16 v[104:105], v202 offset:47616
	s_waitcnt lgkmcnt(14)
	v_mfma_f32_32x32x16_bf16 v[2:17], v[150:153], v[130:133], v[2:17]
	v_add_f32_e32 v50, v56, v106
	v_add_f32_e32 v50, v57, v50
	v_add_f32_e32 v50, v58, v50
	v_add_f32_e32 v50, v59, v50
	v_cvt_pk_bf16_f32 v128, v54, v55
	v_cvt_pk_bf16_f32 v129, v56, v57
	ds_read_b64_tr_b16 v[106:107], v202 offset:44032
	ds_read_b64_tr_b16 v[108:109], v202 offset:44544
	s_waitcnt lgkmcnt(14)
	v_mfma_f32_32x32x16_bf16 v[66:81], v[146:149], v[114:117], v[66:81]
	v_add_f32_e32 v50, v60, v50
	v_add_f32_e32 v50, v61, v50
	v_add_f32_e32 v50, v62, v50
	v_add_f32_e32 v50, v63, v50
	v_cvt_pk_bf16_f32 v134, v58, v59
	v_cvt_pk_bf16_f32 v135, v60, v61
	ds_read_b64_tr_b16 v[130:131], v202 offset:48128
	ds_read_b64_tr_b16 v[132:133], v202 offset:48640
	v_mfma_f32_32x32x16_bf16 v[2:17], v[110:113], v[114:117], v[2:17]
	v_add_f32_e32 v50, v64, v50
	v_add_f32_e32 v50, v65, v50
	v_cvt_pk_bf16_f32 v136, v62, v63
	v_cvt_pk_bf16_f32 v137, v64, v65
	v_max_f32_e32 v51, v66, v67
	s_nop 3
	v_max3_f32 v52, v68, v69, v3
	v_max3_f32 v51, v51, v2, v4
	v_max3_f32 v51, v51, v5, v70
	v_max3_f32 v52, v52, v72, v73
	v_max3_f32 v51, v51, v71, v6
	v_max3_f32 v52, v52, v8, v9
	v_max3_f32 v51, v51, v7, v74
	v_max3_f32 v52, v52, v76, v77
	v_max3_f32 v51, v51, v75, v10
	v_max3_f32 v52, v52, v12, v13
	v_max3_f32 v51, v51, v11, v78
	v_max3_f32 v52, v52, v80, v81
	v_max3_f32 v51, v51, v79, v14
	v_max3_f32 v52, v52, v16, v17
	v_add_f32_e32 v110, v170, v50
	v_max3_f32 v50, v51, v15, v52
	v_mov_b32_e32 v51, v50
	s_nop 1
	v_permlane32_swap_b32_e32 v50, v51
	v_max_f32_e32 v50, v50, v51
	v_cmp_lt_f32_e32 vcc, s51, v50
	s_cmp_lg_u64 vcc, 0
	s_cselect_b64 s[0:1], -1, 0
	s_cbranch_vccnz .LBB0_908
